# attention combine epilogue: 80 serialized ds_bpermute butterfly steps replaced by DPP mov + permlane16_swap (bit-identical sums)
# speedup vs baseline: 1.0044x; 1.0044x over previous
; __device__ __forceinline__ float shx(float v, int o, int lane) { return __int_as_float(__builtin_amdgcn_ds_bpermute((lane ^ o) << 2, __float_as_int(v))); }
; __device__ __forceinline__ int crow(int r, int hi) { return (r & 3) + 8 * (r >> 2) + 4 * hi; }
; __device__ __forceinline__ void attn_unit(LAS unsigned char* lds, bf16_t* Zg, const unsigned char* KVg, int S, int b, int h, int qb, const float* lq1, const float* lk1, const float* lq2, const float* lk2, const float* subln_g, const float* rel_bias, bool dostore = true) {
;     ...
;     __syncthreads();
;     if (mp == 0) {
;         float ss[16];
; #pragma unroll
;         for (int r = 0; r < 16; ++r) { float a = 0.f;
; #pragma unroll
;             for (int db = 0; db < 4; ++db) { const float d = o[db][r] * inv[r] - exch[(32 * qsub + crow(r, hi)) * 128 + db * 32 + r32]; o[db][r] = d; a += d * d; }
;             ss[r] = a; }
; #pragma unroll
;         for (int r = 0; r < 16; ++r) {
; #pragma unroll
;             for (int sft = 1; sft < 32; sft <<= 1) ss[r] += shx(ss[r], sft, lane);
;             ss[r] = (1.0f - LAMBDA_INIT) / sqrtf(ss[r] * (1.0f / 128.0f) + EPS); }
.LBB0_287:
	s_cmpk_gt_u32 s15, 0xff
	s_waitcnt lgkmcnt(0)
	s_barrier
	s_cbranch_scc1 .LBB0_187
	v_or_b32_e32 v0, s84, v211
	v_lshlrev_b32_e32 v0, 9, v0
	v_add3_u32 v0, 0, v82, v0
	ds_read2_b32 v[90:91], v0 offset1:32
	s_waitcnt lgkmcnt(0)
	v_fma_f32 v83, v50, v78, -v90
	v_fma_f32 v50, v34, v78, -v91
	ds_read2_b32 v[90:91], v0 offset0:64 offset1:96
	v_mul_f32_e32 v102, v50, v50
	v_fmac_f32_e32 v102, v83, v83
	s_waitcnt lgkmcnt(0)
	v_fma_f32 v34, v18, v78, -v90
	v_fma_f32 v2, v2, v78, -v91
	ds_read2_b32 v[90:91], v0 offset0:128 offset1:160
	v_add_u32_e32 v18, 0x400, v0
	v_fmac_f32_e32 v102, v34, v34
	v_fmac_f32_e32 v102, v2, v2
	s_waitcnt lgkmcnt(0)
	v_fma_f32 v78, v51, v79, -v90
	v_fma_f32 v51, v35, v79, -v91
	ds_read2_b32 v[90:91], v0 offset0:192 offset1:224
	v_mul_f32_e32 v101, v51, v51
	v_fmac_f32_e32 v101, v78, v78
	s_waitcnt lgkmcnt(0)
	v_fma_f32 v35, v19, v79, -v90
	v_fma_f32 v3, v3, v79, -v91
	ds_read2_b32 v[90:91], v18 offset1:32
	v_add_u32_e32 v19, 0x1000, v0
	v_fmac_f32_e32 v101, v35, v35
	v_fmac_f32_e32 v101, v3, v3
	s_waitcnt lgkmcnt(0)
	v_fma_f32 v79, v52, v80, -v90
	v_fma_f32 v52, v36, v80, -v91
	ds_read2_b32 v[90:91], v18 offset0:64 offset1:96
	v_mul_f32_e32 v100, v52, v52
	v_fmac_f32_e32 v100, v79, v79
	s_waitcnt lgkmcnt(0)
	v_fma_f32 v36, v20, v80, -v90
	v_fma_f32 v4, v4, v80, -v91
	ds_read2_b32 v[90:91], v18 offset0:128 offset1:160
	v_fmac_f32_e32 v100, v36, v36
	v_fmac_f32_e32 v100, v4, v4
	s_waitcnt lgkmcnt(0)
	v_fma_f32 v80, v53, v81, -v90
	v_fma_f32 v53, v37, v81, -v91
	ds_read2_b32 v[90:91], v18 offset0:192 offset1:224
	v_mul_f32_e32 v99, v53, v53
	v_fmac_f32_e32 v99, v80, v80
	s_waitcnt lgkmcnt(0)
	v_fma_f32 v37, v21, v81, -v90
	ds_read2_b32 v[20:21], v19 offset1:32
	v_fma_f32 v5, v5, v81, -v91
	v_fmac_f32_e32 v99, v37, v37
	v_fmac_f32_e32 v99, v5, v5
	s_waitcnt lgkmcnt(0)
	v_fma_f32 v81, v54, v74, -v20
	v_fma_f32 v54, v38, v74, -v21
	ds_read2_b32 v[20:21], v19 offset0:64 offset1:96
	v_mul_f32_e32 v98, v54, v54
	v_fmac_f32_e32 v98, v81, v81
	s_waitcnt lgkmcnt(0)
	v_fma_f32 v38, v22, v74, -v20
	v_fma_f32 v6, v6, v74, -v21
	ds_read2_b32 v[20:21], v19 offset0:128 offset1:160
	v_fmac_f32_e32 v98, v38, v38
	v_fmac_f32_e32 v98, v6, v6
	s_waitcnt lgkmcnt(0)
	v_fma_f32 v74, v55, v75, -v20
	v_fma_f32 v55, v39, v75, -v21
	ds_read2_b32 v[20:21], v19 offset0:192 offset1:224
	v_mul_f32_e32 v97, v55, v55
	v_fmac_f32_e32 v97, v74, v74
	s_waitcnt lgkmcnt(0)
	v_fma_f32 v39, v23, v75, -v20
	v_add_u32_e32 v20, 0x1400, v0
	ds_read2_b32 v[22:23], v20 offset1:32
	v_fma_f32 v7, v7, v75, -v21
	v_add_u32_e32 v21, 0x2000, v0
	v_fmac_f32_e32 v97, v39, v39
	v_fmac_f32_e32 v97, v7, v7
	s_waitcnt lgkmcnt(0)
	v_fma_f32 v75, v56, v76, -v22
	v_fma_f32 v56, v40, v76, -v23
	ds_read2_b32 v[22:23], v20 offset0:64 offset1:96
	v_mul_f32_e32 v96, v56, v56
	v_fmac_f32_e32 v96, v75, v75
	s_waitcnt lgkmcnt(0)
	v_fma_f32 v40, v24, v76, -v22
	v_fma_f32 v8, v8, v76, -v23
	ds_read2_b32 v[22:23], v20 offset0:128 offset1:160
	v_fmac_f32_e32 v96, v40, v40
	v_fmac_f32_e32 v96, v8, v8
	s_waitcnt lgkmcnt(0)
	v_fma_f32 v76, v57, v77, -v22
	v_fma_f32 v57, v41, v77, -v23
	ds_read2_b32 v[22:23], v20 offset0:192 offset1:224
	v_mul_f32_e32 v95, v57, v57
	v_fmac_f32_e32 v95, v76, v76
	s_waitcnt lgkmcnt(0)
	v_fma_f32 v25, v25, v77, -v22
	v_fma_f32 v9, v9, v77, -v23
	ds_read2_b32 v[22:23], v21 offset1:32
	v_fmac_f32_e32 v95, v25, v25
	v_fmac_f32_e32 v95, v9, v9
	s_waitcnt lgkmcnt(0)
	v_fma_f32 v77, v58, v70, -v22
	v_fma_f32 v58, v42, v70, -v23
	ds_read2_b32 v[22:23], v21 offset0:64 offset1:96
	v_mul_f32_e32 v90, v58, v58
	v_fmac_f32_e32 v90, v77, v77
	s_waitcnt lgkmcnt(0)
	v_fma_f32 v26, v26, v70, -v22
	v_fma_f32 v10, v10, v70, -v23
	ds_read2_b32 v[22:23], v21 offset0:128 offset1:160
	v_fmac_f32_e32 v90, v26, v26
	v_fmac_f32_e32 v90, v10, v10
	s_waitcnt lgkmcnt(0)
	v_fma_f32 v70, v59, v71, -v22
	v_fma_f32 v43, v43, v71, -v23
	ds_read2_b32 v[22:23], v21 offset0:192 offset1:224
	v_mul_f32_e32 v93, v43, v43
	v_fmac_f32_e32 v93, v70, v70
	s_waitcnt lgkmcnt(0)
	v_fma_f32 v41, v27, v71, -v22
	v_add_u32_e32 v22, 0x2400, v0
	ds_read2_b32 v[104:105], v22 offset1:32
	v_fma_f32 v11, v11, v71, -v23
	v_add_u32_e32 v23, 0x3000, v0
	s_nop 1
	v_mov_b32_dpp v27, v102 quad_perm:[1,0,3,2] row_mask:0xf bank_mask:0xf
	v_fmac_f32_e32 v93, v41, v41
	s_waitcnt lgkmcnt(0)
	v_fma_f32 v71, v60, v72, -v104
	v_fma_f32 v59, v44, v72, -v105
	ds_read2_b32 v[104:105], v22 offset0:64 offset1:96
	s_waitcnt lgkmcnt(1)
	v_add_f32_e32 v27, v102, v27
	v_fmac_f32_e32 v93, v11, v11
	v_mul_f32_e32 v94, v59, v59
	v_fmac_f32_e32 v94, v71, v71
	s_waitcnt lgkmcnt(0)
	v_fma_f32 v28, v28, v72, -v104
	v_fma_f32 v12, v12, v72, -v105
	ds_read2_b32 v[104:105], v22 offset0:128 offset1:160
	v_fmac_f32_e32 v94, v28, v28
	v_fmac_f32_e32 v94, v12, v12
	s_waitcnt lgkmcnt(0)
	v_fma_f32 v61, v61, v73, -v104
	v_fma_f32 v45, v45, v73, -v105
	ds_read2_b32 v[104:105], v22 offset0:192 offset1:224
	v_mul_f32_e32 v92, v45, v45
	v_fmac_f32_e32 v92, v61, v61
	s_waitcnt lgkmcnt(0)
	v_fma_f32 v29, v29, v73, -v104
	v_fma_f32 v13, v13, v73, -v105
	ds_read2_b32 v[104:105], v23 offset0:64 offset1:96
	ds_read2_b32 v[72:73], v23 offset1:32
	v_fmac_f32_e32 v92, v29, v29
	v_fmac_f32_e32 v92, v13, v13
	s_waitcnt lgkmcnt(1)
	v_fma_f32 v42, v30, v66, -v104
	s_nop 1
	v_mov_b32_dpp v30, v27 quad_perm:[2,3,0,1] row_mask:0xf bank_mask:0xf
	v_fma_f32 v14, v14, v66, -v105
	ds_read2_b32 v[104:105], v23 offset0:128 offset1:160
	s_waitcnt lgkmcnt(1)
	v_fma_f32 v72, v62, v66, -v72
	v_fma_f32 v46, v46, v66, -v73
	s_waitcnt lgkmcnt(1)
	v_add_f32_e32 v27, v27, v30
	s_nop 1
	v_mov_b32_dpp v30, v27 row_half_mirror row_mask:0xf bank_mask:0xf
	s_waitcnt lgkmcnt(0)
; __device__ __forceinline__ float shx(float v, int o, int lane) { return __int_as_float(__builtin_amdgcn_ds_bpermute((lane ^ o) << 2, __float_as_int(v))); }
; __device__ __forceinline__ int crow(int r, int hi) { return (r & 3) + 8 * (r >> 2) + 4 * hi; }
; __device__ __forceinline__ void attn_unit(LAS unsigned char* lds, bf16_t* Zg, const unsigned char* KVg, int S, int b, int h, int qb, const float* lq1, const float* lk1, const float* lq2, const float* lk2, const float* subln_g, const float* rel_bias, bool dostore = true) {
;     ...
;         for (int r = 0; r < 16; ++r) { float a = 0.f;
; #pragma unroll
;             for (int db = 0; db < 4; ++db) { const float d = o[db][r] * inv[r] - exch[(32 * qsub + crow(r, hi)) * 128 + db * 32 + r32]; o[db][r] = d; a += d * d; }
;             ss[r] = a; }
; #pragma unroll
;         for (int r = 0; r < 16; ++r) {
; #pragma unroll
;             for (int sft = 1; sft < 32; sft <<= 1) ss[r] += shx(ss[r], sft, lane);
;             ss[r] = (1.0f - LAMBDA_INIT) / sqrtf(ss[r] * (1.0f / 128.0f) + EPS); }
; #pragma unroll
;         for (int db = 0; db < 4; ++db) { const float sg = subln_g[db * 32 + r32];
; #pragma unroll
;             for (int r = 0; r < 16; ++r) exch[(32 * qsub + crow(r, hi)) * 128 + db * 32 + r32] = o[db][r] * ss[r] * sg; }
	v_fma_f32 v63, v63, v67, -v104
	v_fma_f32 v60, v47, v67, -v105
	ds_read2_b32 v[104:105], v23 offset0:192 offset1:224
	v_mul_f32_e32 v91, v46, v46
	s_waitcnt lgkmcnt(1)
	v_add_f32_e32 v27, v27, v30
	s_nop 1
	v_mov_b32_dpp v30, v27 row_ror:8 row_mask:0xf bank_mask:0xf
	v_fmac_f32_e32 v91, v72, v72
	s_waitcnt lgkmcnt(0)
	v_fma_f32 v24, v15, v67, -v105
	v_add_u32_e32 v15, 0x3400, v0
	v_fma_f32 v31, v31, v67, -v104
	s_waitcnt lgkmcnt(0)
	v_add_f32_e32 v27, v27, v30
	v_mov_b32_e32 v30, v27
	s_nop 1
	v_permlane16_swap_b32_e32 v30, v27
	ds_read2_b32 v[66:67], v15 offset1:32
	v_fmac_f32_e32 v91, v42, v42
	v_fmac_f32_e32 v91, v14, v14
	v_mul_f32_e32 v89, v60, v60
	s_waitcnt lgkmcnt(1)
	v_add_f32_e32 v27, v27, v30
	v_fmamk_f32 v27, v27, 0x3c000000, v206
	v_cmp_gt_f32_e32 vcc, s36, v27
	v_mul_f32_e32 v30, 0x4f800000, v27
	s_waitcnt lgkmcnt(0)
	v_fma_f32 v64, v64, v68, -v66
	v_cndmask_b32_e32 v27, v27, v30, vcc
	v_sqrt_f32_e32 v30, v27
	v_fma_f32 v48, v48, v68, -v67
	ds_read2_b32 v[66:67], v15 offset0:64 offset1:96
	v_fmac_f32_e32 v89, v63, v63
	v_add_u32_e32 v44, -1, v30
	v_fma_f32 v47, -v44, v30, v27
	v_cmp_ge_f32_e64 s[4:5], 0, v47
	v_add_u32_e32 v47, 1, v30
	s_waitcnt lgkmcnt(0)
	v_fma_f32 v32, v32, v68, -v66
	v_cndmask_b32_e64 v44, v30, v44, s[4:5]
	v_fma_f32 v30, -v47, v30, v27
	v_cmp_lt_f32_e64 s[4:5], 0, v30
	v_fma_f32 v16, v16, v68, -v67
	ds_read2_b32 v[66:67], v15 offset0:128 offset1:160
	v_cndmask_b32_e64 v30, v44, v47, s[4:5]
	v_mul_f32_e32 v44, 0x37800000, v30
	v_cndmask_b32_e32 v30, v30, v44, vcc
	v_cmp_class_f32_e32 vcc, v27, v205
	s_waitcnt lgkmcnt(0)
	v_fma_f32 v65, v65, v69, -v66
	v_fma_f32 v49, v49, v69, -v67
	v_cndmask_b32_e32 v27, v30, v27, vcc
	v_div_scale_f32 v30, s[4:5], v27, v27, s95
	v_rcp_f32_e32 v44, v30
	ds_read2_b32 v[66:67], v15 offset0:192 offset1:224
	v_fmac_f32_e32 v89, v31, v31
	v_fmac_f32_e32 v89, v24, v24
	v_fma_f32 v47, -v30, v44, 1.0
	v_fmac_f32_e32 v44, v47, v44
	v_div_scale_f32 v47, vcc, s95, v27, s95
	v_mul_f32_e32 v62, v47, v44
	s_waitcnt lgkmcnt(0)
	v_fma_f32 v33, v33, v69, -v66
	v_fma_f32 v66, -v30, v62, v47
	v_fmac_f32_e32 v62, v66, v44
	v_fma_f32 v30, -v30, v62, v47
	v_div_fmas_f32 v30, v30, v44, v62
	v_div_fixup_f32 v27, v30, v27, s95
	s_nop 1
	v_mov_b32_dpp v30, v101 quad_perm:[1,0,3,2] row_mask:0xf bank_mask:0xf
	v_fma_f32 v17, v17, v69, -v67
	v_mul_f32_e32 v73, v48, v48
	v_fmac_f32_e32 v73, v64, v64
	v_fmac_f32_e32 v73, v32, v32
	s_waitcnt lgkmcnt(0)
	v_add_f32_e32 v30, v101, v30
	s_nop 1
	v_mov_b32_dpp v44, v30 quad_perm:[2,3,0,1] row_mask:0xf bank_mask:0xf
	v_fmac_f32_e32 v73, v16, v16
	v_mul_f32_e32 v68, v49, v49
	v_fmac_f32_e32 v68, v65, v65
	v_fmac_f32_e32 v68, v33, v33
	s_waitcnt lgkmcnt(0)
	v_add_f32_e32 v30, v30, v44
	s_nop 1
	v_mov_b32_dpp v44, v30 row_half_mirror row_mask:0xf bank_mask:0xf
	v_fmac_f32_e32 v68, v17, v17
	v_mul_f32_e32 v83, v83, v27
	v_mul_f32_e32 v50, v50, v27
	v_mul_f32_e32 v34, v34, v27
	s_waitcnt lgkmcnt(0)
	v_add_f32_e32 v30, v30, v44
	s_nop 1
	v_mov_b32_dpp v44, v30 row_ror:8 row_mask:0xf bank_mask:0xf
	v_mul_f32_e32 v2, v2, v27
	s_waitcnt lgkmcnt(0)
	v_add_f32_e32 v30, v30, v44
	v_mov_b32_e32 v44, v30
	s_nop 1
	v_permlane16_swap_b32_e32 v44, v30
	s_waitcnt lgkmcnt(0)
	v_add_f32_e32 v30, v30, v44
	v_fmamk_f32 v30, v30, 0x3c000000, v206
	v_cmp_gt_f32_e32 vcc, s36, v30
	v_mul_f32_e32 v44, 0x4f800000, v30
	s_nop 0
	v_cndmask_b32_e32 v30, v30, v44, vcc
	v_sqrt_f32_e32 v44, v30
	s_nop 0
	v_add_u32_e32 v47, -1, v44
	v_fma_f32 v62, -v47, v44, v30
	v_cmp_ge_f32_e64 s[4:5], 0, v62
	v_add_u32_e32 v62, 1, v44
	s_nop 0
	v_cndmask_b32_e64 v47, v44, v47, s[4:5]
	v_fma_f32 v44, -v62, v44, v30
	v_cmp_lt_f32_e64 s[4:5], 0, v44
	s_nop 1
	v_cndmask_b32_e64 v44, v47, v62, s[4:5]
	v_mul_f32_e32 v47, 0x37800000, v44
	v_cndmask_b32_e32 v44, v44, v47, vcc
	v_cmp_class_f32_e32 vcc, v30, v205
	s_nop 1
	v_cndmask_b32_e32 v30, v44, v30, vcc
	v_div_scale_f32 v44, s[4:5], v30, v30, s95
	v_rcp_f32_e32 v47, v44
	s_nop 0
	v_fma_f32 v62, -v44, v47, 1.0
	v_fmac_f32_e32 v47, v62, v47
	v_div_scale_f32 v62, vcc, s95, v30, s95
	v_mul_f32_e32 v66, v62, v47
	v_fma_f32 v67, -v44, v66, v62
	v_fmac_f32_e32 v66, v67, v47
	v_fma_f32 v44, -v44, v66, v62
	v_div_fmas_f32 v44, v44, v47, v66
	v_div_fixup_f32 v30, v44, v30, s95
	s_nop 1
	v_mov_b32_dpp v44, v100 quad_perm:[1,0,3,2] row_mask:0xf bank_mask:0xf
	v_mul_f32_e32 v78, v78, v30
	s_waitcnt lgkmcnt(0)
	v_add_f32_e32 v44, v100, v44
	s_nop 1
	v_mov_b32_dpp v47, v44 quad_perm:[2,3,0,1] row_mask:0xf bank_mask:0xf
	s_waitcnt lgkmcnt(0)
	v_add_f32_e32 v44, v44, v47
	s_nop 1
	v_mov_b32_dpp v47, v44 row_half_mirror row_mask:0xf bank_mask:0xf
	s_waitcnt lgkmcnt(0)
	v_add_f32_e32 v44, v44, v47
	s_nop 1
	v_mov_b32_dpp v47, v44 row_ror:8 row_mask:0xf bank_mask:0xf
	s_waitcnt lgkmcnt(0)
	v_add_f32_e32 v44, v44, v47
	v_mov_b32_e32 v47, v44
	s_nop 1
	v_permlane16_swap_b32_e32 v47, v44
	s_waitcnt lgkmcnt(0)
	v_add_f32_e32 v44, v44, v47
	v_fmamk_f32 v44, v44, 0x3c000000, v206
	v_cmp_gt_f32_e32 vcc, s36, v44
	v_mul_f32_e32 v47, 0x4f800000, v44
	s_nop 0
	v_cndmask_b32_e32 v44, v44, v47, vcc
	v_sqrt_f32_e32 v47, v44
	s_nop 0
	v_add_u32_e32 v62, -1, v47
	v_fma_f32 v66, -v62, v47, v44
	v_cmp_ge_f32_e64 s[4:5], 0, v66
	v_add_u32_e32 v66, 1, v47
	s_nop 0
	v_cndmask_b32_e64 v62, v47, v62, s[4:5]
	v_fma_f32 v47, -v66, v47, v44
	v_cmp_lt_f32_e64 s[4:5], 0, v47
	s_nop 1
	v_cndmask_b32_e64 v47, v62, v66, s[4:5]
	v_mul_f32_e32 v62, 0x37800000, v47
	v_cndmask_b32_e32 v47, v47, v62, vcc
	v_cmp_class_f32_e32 vcc, v44, v205
	s_nop 1
	v_cndmask_b32_e32 v44, v47, v44, vcc
	v_div_scale_f32 v47, s[4:5], v44, v44, s95
	v_rcp_f32_e32 v62, v47
	s_nop 0
	v_fma_f32 v66, -v47, v62, 1.0
	v_fmac_f32_e32 v62, v66, v62
	v_div_scale_f32 v66, vcc, s95, v44, s95
	v_mul_f32_e32 v67, v66, v62
	v_fma_f32 v69, -v47, v67, v66
	v_fmac_f32_e32 v67, v69, v62
	v_fma_f32 v47, -v47, v67, v66
	v_div_fmas_f32 v47, v47, v62, v67
	v_div_fixup_f32 v44, v47, v44, s95
	s_nop 1
	v_mov_b32_dpp v47, v99 quad_perm:[1,0,3,2] row_mask:0xf bank_mask:0xf
	v_mul_f32_e32 v79, v79, v44
	s_waitcnt lgkmcnt(0)
; __device__ __forceinline__ float shx(float v, int o, int lane) { return __int_as_float(__builtin_amdgcn_ds_bpermute((lane ^ o) << 2, __float_as_int(v))); }
; __device__ __forceinline__ int crow(int r, int hi) { return (r & 3) + 8 * (r >> 2) + 4 * hi; }
; __device__ __forceinline__ void attn_unit(LAS unsigned char* lds, bf16_t* Zg, const unsigned char* KVg, int S, int b, int h, int qb, const float* lq1, const float* lk1, const float* lq2, const float* lk2, const float* subln_g, const float* rel_bias, bool dostore = true) {
;     ...
;         for (int r = 0; r < 16; ++r) {
; #pragma unroll
;             for (int sft = 1; sft < 32; sft <<= 1) ss[r] += shx(ss[r], sft, lane);
;             ss[r] = (1.0f - LAMBDA_INIT) / sqrtf(ss[r] * (1.0f / 128.0f) + EPS); }
; #pragma unroll
;         for (int db = 0; db < 4; ++db) { const float sg = subln_g[db * 32 + r32];
; #pragma unroll
;             for (int r = 0; r < 16; ++r) exch[(32 * qsub + crow(r, hi)) * 128 + db * 32 + r32] = o[db][r] * ss[r] * sg; }
	v_add_f32_e32 v47, v99, v47
	s_nop 1
	v_mov_b32_dpp v62, v47 quad_perm:[2,3,0,1] row_mask:0xf bank_mask:0xf
	s_waitcnt lgkmcnt(0)
	v_add_f32_e32 v47, v47, v62
	s_nop 1
	v_mov_b32_dpp v62, v47 row_half_mirror row_mask:0xf bank_mask:0xf
	s_waitcnt lgkmcnt(0)
	v_add_f32_e32 v47, v47, v62
	s_nop 1
	v_mov_b32_dpp v62, v47 row_ror:8 row_mask:0xf bank_mask:0xf
	s_waitcnt lgkmcnt(0)
	v_add_f32_e32 v47, v47, v62
	v_mov_b32_e32 v62, v47
	s_nop 1
	v_permlane16_swap_b32_e32 v62, v47
	s_waitcnt lgkmcnt(0)
	v_add_f32_e32 v47, v47, v62
	v_fmamk_f32 v47, v47, 0x3c000000, v206
	v_cmp_gt_f32_e32 vcc, s36, v47
	v_mul_f32_e32 v62, 0x4f800000, v47
	s_nop 0
	v_cndmask_b32_e32 v47, v47, v62, vcc
	v_sqrt_f32_e32 v62, v47
	s_nop 0
	v_add_u32_e32 v66, -1, v62
	v_fma_f32 v67, -v66, v62, v47
	v_cmp_ge_f32_e64 s[4:5], 0, v67
	v_add_u32_e32 v67, 1, v62
	s_nop 0
	v_cndmask_b32_e64 v66, v62, v66, s[4:5]
	v_fma_f32 v62, -v67, v62, v47
	v_cmp_lt_f32_e64 s[4:5], 0, v62
	s_nop 1
	v_cndmask_b32_e64 v62, v66, v67, s[4:5]
	v_mul_f32_e32 v66, 0x37800000, v62
	v_cndmask_b32_e32 v62, v62, v66, vcc
	v_cmp_class_f32_e32 vcc, v47, v205
	s_nop 1
	v_cndmask_b32_e32 v47, v62, v47, vcc
	v_div_scale_f32 v62, s[4:5], v47, v47, s95
	v_rcp_f32_e32 v66, v62
	s_nop 0
	v_fma_f32 v67, -v62, v66, 1.0
	v_fmac_f32_e32 v66, v67, v66
	v_div_scale_f32 v67, vcc, s95, v47, s95
	v_mul_f32_e32 v69, v67, v66
	v_fma_f32 v99, -v62, v69, v67
	v_fmac_f32_e32 v69, v99, v66
	v_fma_f32 v62, -v62, v69, v67
	v_div_fmas_f32 v62, v62, v66, v69
	v_div_fixup_f32 v47, v62, v47, s95
	s_nop 1
	v_mov_b32_dpp v62, v98 quad_perm:[1,0,3,2] row_mask:0xf bank_mask:0xf
	v_mul_f32_e32 v80, v80, v47
	s_waitcnt lgkmcnt(0)
	v_add_f32_e32 v62, v98, v62
	s_nop 1
	v_mov_b32_dpp v66, v62 quad_perm:[2,3,0,1] row_mask:0xf bank_mask:0xf
	s_waitcnt lgkmcnt(0)
	v_add_f32_e32 v62, v62, v66
	s_nop 1
	v_mov_b32_dpp v66, v62 row_half_mirror row_mask:0xf bank_mask:0xf
	s_waitcnt lgkmcnt(0)
	v_add_f32_e32 v62, v62, v66
	s_nop 1
	v_mov_b32_dpp v66, v62 row_ror:8 row_mask:0xf bank_mask:0xf
	s_waitcnt lgkmcnt(0)
	v_add_f32_e32 v62, v62, v66
	v_mov_b32_e32 v66, v62
	s_nop 1
	v_permlane16_swap_b32_e32 v66, v62
	s_waitcnt lgkmcnt(0)
	v_add_f32_e32 v62, v62, v66
	v_fmamk_f32 v62, v62, 0x3c000000, v206
	v_cmp_gt_f32_e32 vcc, s36, v62
	v_mul_f32_e32 v66, 0x4f800000, v62
	s_nop 0
	v_cndmask_b32_e32 v62, v62, v66, vcc
	v_sqrt_f32_e32 v66, v62
	s_nop 0
	v_add_u32_e32 v67, -1, v66
	v_fma_f32 v69, -v67, v66, v62
	v_cmp_ge_f32_e64 s[4:5], 0, v69
	v_add_u32_e32 v69, 1, v66
	s_nop 0
	v_cndmask_b32_e64 v67, v66, v67, s[4:5]
	v_fma_f32 v66, -v69, v66, v62
	v_cmp_lt_f32_e64 s[4:5], 0, v66
	s_nop 1
	v_cndmask_b32_e64 v66, v67, v69, s[4:5]
	v_mul_f32_e32 v67, 0x37800000, v66
	v_cndmask_b32_e32 v66, v66, v67, vcc
	v_cmp_class_f32_e32 vcc, v62, v205
	s_nop 1
	v_cndmask_b32_e32 v62, v66, v62, vcc
	v_div_scale_f32 v66, s[4:5], v62, v62, s95
	v_rcp_f32_e32 v67, v66
	s_nop 0
	v_fma_f32 v69, -v66, v67, 1.0
	v_fmac_f32_e32 v67, v69, v67
	v_div_scale_f32 v69, vcc, s95, v62, s95
	v_mul_f32_e32 v98, v69, v67
	v_fma_f32 v99, -v66, v98, v69
	v_fmac_f32_e32 v98, v99, v67
	v_fma_f32 v66, -v66, v98, v69
	v_div_fmas_f32 v66, v66, v67, v98
	v_div_fixup_f32 v62, v66, v62, s95
	s_nop 1
	v_mov_b32_dpp v66, v97 quad_perm:[1,0,3,2] row_mask:0xf bank_mask:0xf
	v_mul_f32_e32 v81, v81, v62
	s_waitcnt lgkmcnt(0)
	v_add_f32_e32 v66, v97, v66
	s_nop 1
	v_mov_b32_dpp v67, v66 quad_perm:[2,3,0,1] row_mask:0xf bank_mask:0xf
	s_waitcnt lgkmcnt(0)
	v_add_f32_e32 v66, v66, v67
	s_nop 1
	v_mov_b32_dpp v67, v66 row_half_mirror row_mask:0xf bank_mask:0xf
	s_waitcnt lgkmcnt(0)
	v_add_f32_e32 v66, v66, v67
	s_nop 1
	v_mov_b32_dpp v67, v66 row_ror:8 row_mask:0xf bank_mask:0xf
	s_waitcnt lgkmcnt(0)
	v_add_f32_e32 v66, v66, v67
	v_mov_b32_e32 v67, v66
	s_nop 1
	v_permlane16_swap_b32_e32 v67, v66
	s_waitcnt lgkmcnt(0)
	v_add_f32_e32 v66, v66, v67
	v_fmamk_f32 v66, v66, 0x3c000000, v206
	v_cmp_gt_f32_e32 vcc, s36, v66
	v_mul_f32_e32 v67, 0x4f800000, v66
	s_nop 0
	v_cndmask_b32_e32 v66, v66, v67, vcc
	v_sqrt_f32_e32 v67, v66
	s_nop 0
	v_add_u32_e32 v69, -1, v67
	v_fma_f32 v97, -v69, v67, v66
	v_cmp_ge_f32_e64 s[4:5], 0, v97
	v_add_u32_e32 v97, 1, v67
	s_nop 0
	v_cndmask_b32_e64 v69, v67, v69, s[4:5]
	v_fma_f32 v67, -v97, v67, v66
	v_cmp_lt_f32_e64 s[4:5], 0, v67
	s_nop 1
	v_cndmask_b32_e64 v67, v69, v97, s[4:5]
	v_mul_f32_e32 v69, 0x37800000, v67
	v_cndmask_b32_e32 v67, v67, v69, vcc
	v_cmp_class_f32_e32 vcc, v66, v205
	s_nop 1
	v_cndmask_b32_e32 v66, v67, v66, vcc
	v_div_scale_f32 v67, s[4:5], v66, v66, s95
	v_rcp_f32_e32 v69, v67
	s_nop 0
	v_fma_f32 v97, -v67, v69, 1.0
	v_fmac_f32_e32 v69, v97, v69
	v_div_scale_f32 v97, vcc, s95, v66, s95
	v_mul_f32_e32 v98, v97, v69
	v_fma_f32 v99, -v67, v98, v97
	v_fmac_f32_e32 v98, v99, v69
	v_fma_f32 v67, -v67, v98, v97
	v_div_fmas_f32 v67, v67, v69, v98
	v_div_fixup_f32 v66, v67, v66, s95
	s_nop 1
	v_mov_b32_dpp v67, v96 quad_perm:[1,0,3,2] row_mask:0xf bank_mask:0xf
	v_mul_f32_e32 v74, v74, v66
	s_waitcnt lgkmcnt(0)
	v_add_f32_e32 v67, v96, v67
	s_nop 1
	v_mov_b32_dpp v69, v67 quad_perm:[2,3,0,1] row_mask:0xf bank_mask:0xf
	s_waitcnt lgkmcnt(0)
	v_add_f32_e32 v67, v67, v69
	s_nop 1
	v_mov_b32_dpp v69, v67 row_half_mirror row_mask:0xf bank_mask:0xf
	s_waitcnt lgkmcnt(0)
	v_add_f32_e32 v67, v67, v69
	s_nop 1
	v_mov_b32_dpp v69, v67 row_ror:8 row_mask:0xf bank_mask:0xf
	s_waitcnt lgkmcnt(0)
	v_add_f32_e32 v67, v67, v69
	v_mov_b32_e32 v69, v67
	s_nop 1
	v_permlane16_swap_b32_e32 v69, v67
	s_waitcnt lgkmcnt(0)
; __device__ __forceinline__ float shx(float v, int o, int lane) { return __int_as_float(__builtin_amdgcn_ds_bpermute((lane ^ o) << 2, __float_as_int(v))); }
; __device__ __forceinline__ int crow(int r, int hi) { return (r & 3) + 8 * (r >> 2) + 4 * hi; }
; __device__ __forceinline__ void attn_unit(LAS unsigned char* lds, bf16_t* Zg, const unsigned char* KVg, int S, int b, int h, int qb, const float* lq1, const float* lk1, const float* lq2, const float* lk2, const float* subln_g, const float* rel_bias, bool dostore = true) {
;     ...
;         for (int r = 0; r < 16; ++r) {
; #pragma unroll
;             for (int sft = 1; sft < 32; sft <<= 1) ss[r] += shx(ss[r], sft, lane);
;             ss[r] = (1.0f - LAMBDA_INIT) / sqrtf(ss[r] * (1.0f / 128.0f) + EPS); }
; #pragma unroll
;         for (int db = 0; db < 4; ++db) { const float sg = subln_g[db * 32 + r32];
; #pragma unroll
;             for (int r = 0; r < 16; ++r) exch[(32 * qsub + crow(r, hi)) * 128 + db * 32 + r32] = o[db][r] * ss[r] * sg; }
	v_add_f32_e32 v67, v67, v69
	v_fmamk_f32 v67, v67, 0x3c000000, v206
	v_cmp_gt_f32_e32 vcc, s36, v67
	v_mul_f32_e32 v69, 0x4f800000, v67
	s_nop 0
	v_cndmask_b32_e32 v67, v67, v69, vcc
	v_sqrt_f32_e32 v69, v67
	s_nop 0
	v_add_u32_e32 v96, -1, v69
	v_fma_f32 v97, -v96, v69, v67
	v_cmp_ge_f32_e64 s[4:5], 0, v97
	v_add_u32_e32 v97, 1, v69
	s_nop 0
	v_cndmask_b32_e64 v96, v69, v96, s[4:5]
	v_fma_f32 v69, -v97, v69, v67
	v_cmp_lt_f32_e64 s[4:5], 0, v69
	s_nop 1
	v_cndmask_b32_e64 v69, v96, v97, s[4:5]
	v_mul_f32_e32 v96, 0x37800000, v69
	v_cndmask_b32_e32 v69, v69, v96, vcc
	v_cmp_class_f32_e32 vcc, v67, v205
	s_nop 1
	v_cndmask_b32_e32 v67, v69, v67, vcc
	v_div_scale_f32 v69, s[4:5], v67, v67, s95
	v_rcp_f32_e32 v96, v69
	s_nop 0
	v_fma_f32 v97, -v69, v96, 1.0
	v_fmac_f32_e32 v96, v97, v96
	v_div_scale_f32 v97, vcc, s95, v67, s95
	v_mul_f32_e32 v98, v97, v96
	v_fma_f32 v99, -v69, v98, v97
	v_fmac_f32_e32 v98, v99, v96
	v_fma_f32 v69, -v69, v98, v97
	v_div_fmas_f32 v69, v69, v96, v98
	v_div_fixup_f32 v67, v69, v67, s95
	s_nop 1
	v_mov_b32_dpp v69, v95 quad_perm:[1,0,3,2] row_mask:0xf bank_mask:0xf
	v_mul_f32_e32 v75, v75, v67
	s_waitcnt lgkmcnt(0)
	v_add_f32_e32 v69, v95, v69
	s_nop 1
	v_mov_b32_dpp v95, v69 quad_perm:[2,3,0,1] row_mask:0xf bank_mask:0xf
	s_waitcnt lgkmcnt(0)
	v_add_f32_e32 v69, v69, v95
	s_nop 1
	v_mov_b32_dpp v95, v69 row_half_mirror row_mask:0xf bank_mask:0xf
	s_waitcnt lgkmcnt(0)
	v_add_f32_e32 v69, v69, v95
	s_nop 1
	v_mov_b32_dpp v95, v69 row_ror:8 row_mask:0xf bank_mask:0xf
	s_waitcnt lgkmcnt(0)
	v_add_f32_e32 v69, v69, v95
	v_mov_b32_e32 v95, v69
	s_nop 1
	v_permlane16_swap_b32_e32 v95, v69
	s_waitcnt lgkmcnt(0)
	v_add_f32_e32 v69, v69, v95
	v_fmamk_f32 v69, v69, 0x3c000000, v206
	v_cmp_gt_f32_e32 vcc, s36, v69
	v_mul_f32_e32 v95, 0x4f800000, v69
	s_nop 0
	v_cndmask_b32_e32 v69, v69, v95, vcc
	v_sqrt_f32_e32 v95, v69
	s_nop 0
	v_add_u32_e32 v96, -1, v95
	v_fma_f32 v97, -v96, v95, v69
	v_cmp_ge_f32_e64 s[4:5], 0, v97
	v_add_u32_e32 v97, 1, v95
	s_nop 0
	v_cndmask_b32_e64 v96, v95, v96, s[4:5]
	v_fma_f32 v95, -v97, v95, v69
	v_cmp_lt_f32_e64 s[4:5], 0, v95
	s_nop 1
	v_cndmask_b32_e64 v95, v96, v97, s[4:5]
	v_mul_f32_e32 v96, 0x37800000, v95
	v_cndmask_b32_e32 v95, v95, v96, vcc
	v_cmp_class_f32_e32 vcc, v69, v205
	s_nop 1
	v_cndmask_b32_e32 v69, v95, v69, vcc
	v_div_scale_f32 v95, s[4:5], v69, v69, s95
	v_rcp_f32_e32 v96, v95
	s_nop 0
	v_fma_f32 v97, -v95, v96, 1.0
	v_fmac_f32_e32 v96, v97, v96
	v_div_scale_f32 v97, vcc, s95, v69, s95
	v_mul_f32_e32 v98, v97, v96
	v_fma_f32 v99, -v95, v98, v97
	v_fmac_f32_e32 v98, v99, v96
	v_fma_f32 v95, -v95, v98, v97
	v_div_fmas_f32 v95, v95, v96, v98
	v_div_fixup_f32 v69, v95, v69, s95
	s_nop 1
	v_mov_b32_dpp v95, v90 quad_perm:[1,0,3,2] row_mask:0xf bank_mask:0xf
	v_mul_f32_e32 v76, v76, v69
	v_mul_f32_e32 v25, v25, v69
	s_waitcnt lgkmcnt(0)
	v_add_f32_e32 v90, v90, v95
	s_nop 1
	v_mov_b32_dpp v95, v90 quad_perm:[2,3,0,1] row_mask:0xf bank_mask:0xf
	s_waitcnt lgkmcnt(0)
	v_add_f32_e32 v90, v90, v95
	s_nop 1
	v_mov_b32_dpp v95, v90 row_half_mirror row_mask:0xf bank_mask:0xf
	s_waitcnt lgkmcnt(0)
	v_add_f32_e32 v90, v90, v95
	s_nop 1
	v_mov_b32_dpp v95, v90 row_ror:8 row_mask:0xf bank_mask:0xf
	s_waitcnt lgkmcnt(0)
	v_add_f32_e32 v90, v90, v95
	v_mov_b32_e32 v95, v90
	s_nop 1
	v_permlane16_swap_b32_e32 v95, v90
	s_waitcnt lgkmcnt(0)
	v_add_f32_e32 v90, v90, v95
	v_fmamk_f32 v90, v90, 0x3c000000, v206
	v_cmp_gt_f32_e32 vcc, s36, v90
	v_mul_f32_e32 v95, 0x4f800000, v90
	s_nop 0
	v_cndmask_b32_e32 v90, v90, v95, vcc
	v_sqrt_f32_e32 v95, v90
	s_nop 0
	v_add_u32_e32 v96, -1, v95
	v_fma_f32 v97, -v96, v95, v90
	v_cmp_ge_f32_e64 s[4:5], 0, v97
	v_add_u32_e32 v97, 1, v95
	s_nop 0
	v_cndmask_b32_e64 v96, v95, v96, s[4:5]
	v_fma_f32 v95, -v97, v95, v90
	v_cmp_lt_f32_e64 s[4:5], 0, v95
	s_nop 1
	v_cndmask_b32_e64 v95, v96, v97, s[4:5]
	v_mul_f32_e32 v96, 0x37800000, v95
	v_cndmask_b32_e32 v95, v95, v96, vcc
	v_cmp_class_f32_e32 vcc, v90, v205
	s_nop 1
	v_cndmask_b32_e32 v90, v95, v90, vcc
	v_div_scale_f32 v95, s[4:5], v90, v90, s95
	v_rcp_f32_e32 v96, v95
	s_nop 0
	v_fma_f32 v97, -v95, v96, 1.0
	v_fmac_f32_e32 v96, v97, v96
	v_div_scale_f32 v97, vcc, s95, v90, s95
	v_mul_f32_e32 v98, v97, v96
	v_fma_f32 v99, -v95, v98, v97
	v_fmac_f32_e32 v98, v99, v96
	v_fma_f32 v95, -v95, v98, v97
	v_div_fmas_f32 v95, v95, v96, v98
	v_div_fixup_f32 v90, v95, v90, s95
	s_nop 1
	v_mov_b32_dpp v95, v93 quad_perm:[1,0,3,2] row_mask:0xf bank_mask:0xf
	v_mul_f32_e32 v77, v77, v90
	s_waitcnt lgkmcnt(0)
	v_add_f32_e32 v93, v93, v95
	s_nop 1
	v_mov_b32_dpp v95, v93 quad_perm:[2,3,0,1] row_mask:0xf bank_mask:0xf
	s_waitcnt lgkmcnt(0)
	v_add_f32_e32 v93, v93, v95
	s_nop 1
	v_mov_b32_dpp v95, v93 row_half_mirror row_mask:0xf bank_mask:0xf
	s_waitcnt lgkmcnt(0)
	v_add_f32_e32 v93, v93, v95
	s_nop 1
	v_mov_b32_dpp v95, v93 row_ror:8 row_mask:0xf bank_mask:0xf
	s_waitcnt lgkmcnt(0)
	v_add_f32_e32 v93, v93, v95
	v_mov_b32_e32 v95, v93
	s_nop 1
	v_permlane16_swap_b32_e32 v95, v93
	s_waitcnt lgkmcnt(0)
	v_add_f32_e32 v93, v93, v95
	v_fmamk_f32 v93, v93, 0x3c000000, v206
	v_cmp_gt_f32_e32 vcc, s36, v93
	v_mul_f32_e32 v95, 0x4f800000, v93
	s_nop 0
	v_cndmask_b32_e32 v93, v93, v95, vcc
	v_sqrt_f32_e32 v95, v93
	s_nop 0
	v_add_u32_e32 v96, -1, v95
	v_fma_f32 v97, -v96, v95, v93
	v_cmp_ge_f32_e64 s[4:5], 0, v97
	v_add_u32_e32 v97, 1, v95
	s_nop 0
	v_cndmask_b32_e64 v96, v95, v96, s[4:5]
	v_fma_f32 v95, -v97, v95, v93
	v_cmp_lt_f32_e64 s[4:5], 0, v95
	s_nop 1
	v_cndmask_b32_e64 v95, v96, v97, s[4:5]
	v_mul_f32_e32 v96, 0x37800000, v95
	v_cndmask_b32_e32 v95, v95, v96, vcc
	v_cmp_class_f32_e32 vcc, v93, v205
	s_nop 1
	v_cndmask_b32_e32 v93, v95, v93, vcc
	v_div_scale_f32 v95, s[4:5], v93, v93, s95
	v_rcp_f32_e32 v96, v95
	s_nop 0
	v_fma_f32 v97, -v95, v96, 1.0
	v_fmac_f32_e32 v96, v97, v96
	v_div_scale_f32 v97, vcc, s95, v93, s95
	v_mul_f32_e32 v98, v97, v96
	v_fma_f32 v99, -v95, v98, v97
	v_fmac_f32_e32 v98, v99, v96
	v_fma_f32 v95, -v95, v98, v97
	v_div_fmas_f32 v95, v95, v96, v98
	v_div_fixup_f32 v93, v95, v93, s95
	s_nop 1
	v_mov_b32_dpp v95, v94 quad_perm:[1,0,3,2] row_mask:0xf bank_mask:0xf
	v_mul_f32_e32 v70, v70, v93
	v_mul_f32_e32 v43, v43, v93
	s_waitcnt lgkmcnt(0)
; __device__ __forceinline__ float shx(float v, int o, int lane) { return __int_as_float(__builtin_amdgcn_ds_bpermute((lane ^ o) << 2, __float_as_int(v))); }
; __device__ __forceinline__ int crow(int r, int hi) { return (r & 3) + 8 * (r >> 2) + 4 * hi; }
; __device__ __forceinline__ void attn_unit(LAS unsigned char* lds, bf16_t* Zg, const unsigned char* KVg, int S, int b, int h, int qb, const float* lq1, const float* lk1, const float* lq2, const float* lk2, const float* subln_g, const float* rel_bias, bool dostore = true) {
;     ...
;         for (int r = 0; r < 16; ++r) {
; #pragma unroll
;             for (int sft = 1; sft < 32; sft <<= 1) ss[r] += shx(ss[r], sft, lane);
;             ss[r] = (1.0f - LAMBDA_INIT) / sqrtf(ss[r] * (1.0f / 128.0f) + EPS); }
; #pragma unroll
;         for (int db = 0; db < 4; ++db) { const float sg = subln_g[db * 32 + r32];
; #pragma unroll
;             for (int r = 0; r < 16; ++r) exch[(32 * qsub + crow(r, hi)) * 128 + db * 32 + r32] = o[db][r] * ss[r] * sg; }
	v_add_f32_e32 v94, v94, v95
	s_nop 1
	v_mov_b32_dpp v95, v94 quad_perm:[2,3,0,1] row_mask:0xf bank_mask:0xf
	s_waitcnt lgkmcnt(0)
	v_add_f32_e32 v94, v94, v95
	s_nop 1
	v_mov_b32_dpp v95, v94 row_half_mirror row_mask:0xf bank_mask:0xf
	s_waitcnt lgkmcnt(0)
	v_add_f32_e32 v94, v94, v95
	s_nop 1
	v_mov_b32_dpp v95, v94 row_ror:8 row_mask:0xf bank_mask:0xf
	s_waitcnt lgkmcnt(0)
	v_add_f32_e32 v94, v94, v95
	v_mov_b32_e32 v95, v94
	s_nop 1
	v_permlane16_swap_b32_e32 v95, v94
	s_waitcnt lgkmcnt(0)
	v_add_f32_e32 v94, v94, v95
	v_fmamk_f32 v94, v94, 0x3c000000, v206
	v_cmp_gt_f32_e32 vcc, s36, v94
	v_mul_f32_e32 v95, 0x4f800000, v94
	s_nop 0
	v_cndmask_b32_e32 v94, v94, v95, vcc
	v_sqrt_f32_e32 v95, v94
	s_nop 0
	v_add_u32_e32 v96, -1, v95
	v_fma_f32 v97, -v96, v95, v94
	v_cmp_ge_f32_e64 s[4:5], 0, v97
	v_add_u32_e32 v97, 1, v95
	s_nop 0
	v_cndmask_b32_e64 v96, v95, v96, s[4:5]
	v_fma_f32 v95, -v97, v95, v94
	v_cmp_lt_f32_e64 s[4:5], 0, v95
	s_nop 1
	v_cndmask_b32_e64 v95, v96, v97, s[4:5]
	v_mul_f32_e32 v96, 0x37800000, v95
	v_cndmask_b32_e32 v95, v95, v96, vcc
	v_cmp_class_f32_e32 vcc, v94, v205
	s_nop 1
	v_cndmask_b32_e32 v94, v95, v94, vcc
	v_div_scale_f32 v95, s[4:5], v94, v94, s95
	v_rcp_f32_e32 v96, v95
	s_nop 0
	v_fma_f32 v97, -v95, v96, 1.0
	v_fmac_f32_e32 v96, v97, v96
	v_div_scale_f32 v97, vcc, s95, v94, s95
	v_mul_f32_e32 v98, v97, v96
	v_fma_f32 v99, -v95, v98, v97
	v_fmac_f32_e32 v98, v99, v96
	v_fma_f32 v95, -v95, v98, v97
	v_div_fmas_f32 v95, v95, v96, v98
	v_div_fixup_f32 v94, v95, v94, s95
	s_nop 1
	v_mov_b32_dpp v95, v92 quad_perm:[1,0,3,2] row_mask:0xf bank_mask:0xf
	v_mul_f32_e32 v71, v71, v94
	s_waitcnt lgkmcnt(0)
	v_add_f32_e32 v92, v92, v95
	s_nop 1
	v_mov_b32_dpp v95, v92 quad_perm:[2,3,0,1] row_mask:0xf bank_mask:0xf
	s_waitcnt lgkmcnt(0)
	v_add_f32_e32 v92, v92, v95
	s_nop 1
	v_mov_b32_dpp v95, v92 row_half_mirror row_mask:0xf bank_mask:0xf
	s_waitcnt lgkmcnt(0)
	v_add_f32_e32 v92, v92, v95
	s_nop 1
	v_mov_b32_dpp v95, v92 row_ror:8 row_mask:0xf bank_mask:0xf
	s_waitcnt lgkmcnt(0)
	v_add_f32_e32 v92, v92, v95
	v_mov_b32_e32 v95, v92
	s_nop 1
	v_permlane16_swap_b32_e32 v95, v92
	s_waitcnt lgkmcnt(0)
	v_add_f32_e32 v92, v92, v95
	v_fmamk_f32 v92, v92, 0x3c000000, v206
	v_cmp_gt_f32_e32 vcc, s36, v92
	v_mul_f32_e32 v95, 0x4f800000, v92
	s_nop 0
	v_cndmask_b32_e32 v92, v92, v95, vcc
	v_sqrt_f32_e32 v95, v92
	s_nop 0
	v_add_u32_e32 v96, -1, v95
	v_fma_f32 v97, -v96, v95, v92
	v_cmp_ge_f32_e64 s[4:5], 0, v97
	v_add_u32_e32 v97, 1, v95
	s_nop 0
	v_cndmask_b32_e64 v96, v95, v96, s[4:5]
	v_fma_f32 v95, -v97, v95, v92
	v_cmp_lt_f32_e64 s[4:5], 0, v95
	s_nop 1
	v_cndmask_b32_e64 v95, v96, v97, s[4:5]
	v_mul_f32_e32 v96, 0x37800000, v95
	v_cndmask_b32_e32 v95, v95, v96, vcc
	v_cmp_class_f32_e32 vcc, v92, v205
	s_nop 1
	v_cndmask_b32_e32 v92, v95, v92, vcc
	v_div_scale_f32 v95, s[4:5], v92, v92, s95
	v_rcp_f32_e32 v96, v95
	s_nop 0
	v_fma_f32 v97, -v95, v96, 1.0
	v_fmac_f32_e32 v96, v97, v96
	v_div_scale_f32 v97, vcc, s95, v92, s95
	v_mul_f32_e32 v98, v97, v96
	v_fma_f32 v99, -v95, v98, v97
	v_fmac_f32_e32 v98, v99, v96
	v_fma_f32 v95, -v95, v98, v97
	v_div_fmas_f32 v95, v95, v96, v98
	v_div_fixup_f32 v92, v95, v92, s95
	s_nop 1
	v_mov_b32_dpp v95, v91 quad_perm:[1,0,3,2] row_mask:0xf bank_mask:0xf
	v_mul_f32_e32 v61, v61, v92
	s_waitcnt lgkmcnt(0)
	v_add_f32_e32 v91, v91, v95
	s_nop 1
	v_mov_b32_dpp v95, v91 quad_perm:[2,3,0,1] row_mask:0xf bank_mask:0xf
	s_waitcnt lgkmcnt(0)
	v_add_f32_e32 v91, v91, v95
	s_nop 1
	v_mov_b32_dpp v95, v91 row_half_mirror row_mask:0xf bank_mask:0xf
	s_waitcnt lgkmcnt(0)
	v_add_f32_e32 v91, v91, v95
	s_nop 1
	v_mov_b32_dpp v95, v91 row_ror:8 row_mask:0xf bank_mask:0xf
	s_waitcnt lgkmcnt(0)
	v_add_f32_e32 v91, v91, v95
	v_mov_b32_e32 v95, v91
	s_nop 1
	v_permlane16_swap_b32_e32 v95, v91
	s_waitcnt lgkmcnt(0)
	v_add_f32_e32 v91, v91, v95
	v_fmamk_f32 v91, v91, 0x3c000000, v206
	v_cmp_gt_f32_e32 vcc, s36, v91
	v_mul_f32_e32 v95, 0x4f800000, v91
	s_nop 0
	v_cndmask_b32_e32 v91, v91, v95, vcc
	v_sqrt_f32_e32 v95, v91
	s_nop 0
	v_add_u32_e32 v96, -1, v95
	v_fma_f32 v97, -v96, v95, v91
	v_cmp_ge_f32_e64 s[4:5], 0, v97
	v_add_u32_e32 v97, 1, v95
	s_nop 0
	v_cndmask_b32_e64 v96, v95, v96, s[4:5]
	v_fma_f32 v95, -v97, v95, v91
	v_cmp_lt_f32_e64 s[4:5], 0, v95
	s_nop 1
	v_cndmask_b32_e64 v95, v96, v97, s[4:5]
	v_mul_f32_e32 v96, 0x37800000, v95
	v_cndmask_b32_e32 v95, v95, v96, vcc
	v_cmp_class_f32_e32 vcc, v91, v205
	s_nop 1
	v_cndmask_b32_e32 v91, v95, v91, vcc
	v_div_scale_f32 v95, s[4:5], v91, v91, s95
	v_rcp_f32_e32 v96, v95
	s_nop 0
	v_fma_f32 v97, -v95, v96, 1.0
	v_fmac_f32_e32 v96, v97, v96
	v_div_scale_f32 v97, vcc, s95, v91, s95
	v_mul_f32_e32 v98, v97, v96
	v_fma_f32 v99, -v95, v98, v97
	v_fmac_f32_e32 v98, v99, v96
	v_fma_f32 v95, -v95, v98, v97
	v_div_fmas_f32 v95, v95, v96, v98
	v_div_fixup_f32 v91, v95, v91, s95
	s_nop 1
	v_mov_b32_dpp v95, v89 quad_perm:[1,0,3,2] row_mask:0xf bank_mask:0xf
	v_mul_f32_e32 v72, v72, v91
	s_waitcnt lgkmcnt(0)
	v_add_f32_e32 v89, v89, v95
	s_nop 1
	v_mov_b32_dpp v95, v89 quad_perm:[2,3,0,1] row_mask:0xf bank_mask:0xf
	s_waitcnt lgkmcnt(0)
	v_add_f32_e32 v89, v89, v95
	s_nop 1
	v_mov_b32_dpp v95, v89 row_half_mirror row_mask:0xf bank_mask:0xf
	s_waitcnt lgkmcnt(0)
	v_add_f32_e32 v89, v89, v95
	s_nop 1
	v_mov_b32_dpp v95, v89 row_ror:8 row_mask:0xf bank_mask:0xf
	s_waitcnt lgkmcnt(0)
	v_add_f32_e32 v89, v89, v95
	v_mov_b32_e32 v95, v89
	s_nop 1
	v_permlane16_swap_b32_e32 v95, v89
	s_waitcnt lgkmcnt(0)
; __device__ __forceinline__ float shx(float v, int o, int lane) { return __int_as_float(__builtin_amdgcn_ds_bpermute((lane ^ o) << 2, __float_as_int(v))); }
; __device__ __forceinline__ void attn_unit(LAS unsigned char* lds, bf16_t* Zg, const unsigned char* KVg, int S, int b, int h, int qb, const float* lq1, const float* lk1, const float* lq2, const float* lk2, const float* subln_g, const float* rel_bias, bool dostore = true) {
;     ...
;         for (int r = 0; r < 16; ++r) {
; #pragma unroll
;             for (int sft = 1; sft < 32; sft <<= 1) ss[r] += shx(ss[r], sft, lane);
;             ss[r] = (1.0f - LAMBDA_INIT) / sqrtf(ss[r] * (1.0f / 128.0f) + EPS); }
; #pragma unroll
;         for (int db = 0; db < 4; ++db) { const float sg = subln_g[db * 32 + r32];
	v_add_f32_e32 v89, v89, v95
	v_fmamk_f32 v89, v89, 0x3c000000, v206
	v_cmp_gt_f32_e32 vcc, s36, v89
	v_mul_f32_e32 v95, 0x4f800000, v89
	s_nop 0
	v_cndmask_b32_e32 v89, v89, v95, vcc
	v_sqrt_f32_e32 v95, v89
	s_nop 0
	v_add_u32_e32 v96, -1, v95
	v_fma_f32 v97, -v96, v95, v89
	v_cmp_ge_f32_e64 s[4:5], 0, v97
	v_add_u32_e32 v97, 1, v95
	s_nop 0
	v_cndmask_b32_e64 v96, v95, v96, s[4:5]
	v_fma_f32 v95, -v97, v95, v89
	v_cmp_lt_f32_e64 s[4:5], 0, v95
	s_nop 1
	v_cndmask_b32_e64 v95, v96, v97, s[4:5]
	v_mul_f32_e32 v96, 0x37800000, v95
	v_cndmask_b32_e32 v95, v95, v96, vcc
	v_cmp_class_f32_e32 vcc, v89, v205
	s_nop 1
	v_cndmask_b32_e32 v89, v95, v89, vcc
	v_div_scale_f32 v95, s[4:5], v89, v89, s95
	v_rcp_f32_e32 v96, v95
	s_nop 0
	v_fma_f32 v97, -v95, v96, 1.0
	v_fmac_f32_e32 v96, v97, v96
	v_div_scale_f32 v97, vcc, s95, v89, s95
	v_mul_f32_e32 v98, v97, v96
	v_fma_f32 v99, -v95, v98, v97
	v_fmac_f32_e32 v98, v99, v96
	v_fma_f32 v95, -v95, v98, v97
	v_div_fmas_f32 v95, v95, v96, v98
	v_div_fixup_f32 v89, v95, v89, s95
	s_nop 1
	v_mov_b32_dpp v95, v73 quad_perm:[1,0,3,2] row_mask:0xf bank_mask:0xf
	s_nop 1
	v_mov_b32_dpp v84, v68 quad_perm:[1,0,3,2] row_mask:0xf bank_mask:0xf
	v_mul_f32_e32 v63, v63, v89
	s_waitcnt lgkmcnt(0)
	v_add_f32_e32 v73, v73, v95
	s_nop 1
	v_mov_b32_dpp v95, v73 quad_perm:[2,3,0,1] row_mask:0xf bank_mask:0xf
	s_waitcnt lgkmcnt(0)
	v_add_f32_e32 v68, v68, v84
	s_nop 1
	v_mov_b32_dpp v84, v68 quad_perm:[2,3,0,1] row_mask:0xf bank_mask:0xf
	s_waitcnt lgkmcnt(0)
	v_add_f32_e32 v73, v73, v95
	s_nop 1
	v_mov_b32_dpp v95, v73 row_half_mirror row_mask:0xf bank_mask:0xf
	s_waitcnt lgkmcnt(0)
	v_add_f32_e32 v68, v68, v84
	s_nop 1
	v_mov_b32_dpp v84, v68 row_half_mirror row_mask:0xf bank_mask:0xf
	s_waitcnt lgkmcnt(0)
	v_add_f32_e32 v73, v73, v95
	s_nop 1
	v_mov_b32_dpp v95, v73 row_ror:8 row_mask:0xf bank_mask:0xf
	s_waitcnt lgkmcnt(0)
	v_add_f32_e32 v68, v68, v84
	s_nop 1
	v_mov_b32_dpp v84, v68 row_ror:8 row_mask:0xf bank_mask:0xf
	s_waitcnt lgkmcnt(0)
	v_add_f32_e32 v73, v73, v95
	v_mov_b32_e32 v95, v73
	s_nop 1
	v_permlane16_swap_b32_e32 v95, v73
	s_waitcnt lgkmcnt(0)
	v_add_f32_e32 v68, v68, v84
	v_mov_b32_e32 v84, v68
	s_nop 1
	v_permlane16_swap_b32_e32 v84, v68
	s_waitcnt lgkmcnt(0)
	v_add_f32_e32 v73, v73, v95
	v_fmamk_f32 v73, v73, 0x3c000000, v206
	v_cmp_gt_f32_e32 vcc, s36, v73
	v_mul_f32_e32 v95, 0x4f800000, v73
	s_waitcnt lgkmcnt(0)
	v_add_f32_e32 v68, v68, v84
	v_cndmask_b32_e32 v73, v73, v95, vcc
	v_sqrt_f32_e32 v95, v73
	v_fmamk_f32 v68, v68, 0x3c000000, v206
	v_mul_f32_e32 v84, 0x4f800000, v68
	v_add_u32_e32 v96, -1, v95
	v_fma_f32 v97, -v96, v95, v73
	v_cmp_ge_f32_e64 s[4:5], 0, v97
	v_add_u32_e32 v97, 1, v95
	s_nop 0
	v_cndmask_b32_e64 v96, v95, v96, s[4:5]
	v_fma_f32 v95, -v97, v95, v73
	v_cmp_lt_f32_e64 s[4:5], 0, v95
	s_nop 1
	v_cndmask_b32_e64 v95, v96, v97, s[4:5]
	v_mul_f32_e32 v96, 0x37800000, v95
	v_cndmask_b32_e32 v95, v95, v96, vcc
	v_cmp_class_f32_e32 vcc, v73, v205
	s_nop 1
	v_cndmask_b32_e32 v73, v95, v73, vcc
	v_div_scale_f32 v95, s[4:5], v73, v73, s95
	v_rcp_f32_e32 v96, v95
	s_nop 0
	v_fma_f32 v97, -v95, v96, 1.0
	v_fmac_f32_e32 v96, v97, v96
	v_div_scale_f32 v97, vcc, s95, v73, s95
	v_mul_f32_e32 v98, v97, v96
	v_fma_f32 v99, -v95, v98, v97
	v_fmac_f32_e32 v98, v99, v96
	v_fma_f32 v95, -v95, v98, v97
	v_div_fmas_f32 v95, v95, v96, v98
	v_cmp_gt_f32_e32 vcc, s36, v68
	v_div_fixup_f32 v73, v95, v73, s95
	v_mul_f32_e32 v64, v64, v73
	v_cndmask_b32_e32 v68, v68, v84, vcc
	v_sqrt_f32_e32 v84, v68
	s_nop 0
	v_add_u32_e32 v85, -1, v84
	v_fma_f32 v86, -v85, v84, v68
	v_cmp_ge_f32_e64 s[4:5], 0, v86
	v_add_u32_e32 v86, 1, v84
	s_nop 0
	v_cndmask_b32_e64 v85, v84, v85, s[4:5]
	v_fma_f32 v84, -v86, v84, v68
	v_cmp_lt_f32_e64 s[4:5], 0, v84
	s_nop 1
	v_cndmask_b32_e64 v84, v85, v86, s[4:5]
	v_mul_f32_e32 v85, 0x37800000, v84
	v_cndmask_b32_e32 v84, v84, v85, vcc
	v_cmp_class_f32_e32 vcc, v68, v205
	s_nop 1
	v_cndmask_b32_e32 v68, v84, v68, vcc
	v_div_scale_f32 v84, s[4:5], v68, v68, s95
	v_rcp_f32_e32 v85, v84
	s_nop 0
	v_fma_f32 v86, -v84, v85, 1.0
	v_fmac_f32_e32 v85, v86, v85
	v_div_scale_f32 v86, vcc, s95, v68, s95
	v_mul_f32_e32 v87, v86, v85
	v_fma_f32 v88, -v84, v87, v86
	v_fmac_f32_e32 v87, v88, v85
	v_fma_f32 v84, -v84, v87, v86
	v_div_fmas_f32 v84, v84, v85, v87
	v_div_fixup_f32 v68, v84, v68, s95
	global_load_dword v84, v82, s[68:69]
	global_load_dword v85, v82, s[68:69] offset:128
	global_load_dword v86, v82, s[68:69] offset:256
	global_load_dword v87, v82, s[68:69] offset:384
	v_mul_f32_e32 v65, v65, v68
	s_waitcnt vmcnt(0)
; __device__ __forceinline__ int crow(int r, int hi) { return (r & 3) + 8 * (r >> 2) + 4 * hi; }
; __device__ __forceinline__ void attn_unit(LAS unsigned char* lds, bf16_t* Zg, const unsigned char* KVg, int S, int b, int h, int qb, const float* lq1, const float* lk1, const float* lq2, const float* lk2, const float* subln_g, const float* rel_bias, bool dostore = true) {
;     ...
;         for (int db = 0; db < 4; ++db) { const float sg = subln_g[db * 32 + r32];
; #pragma unroll
;             for (int r = 0; r < 16; ++r) exch[(32 * qsub + crow(r, hi)) * 128 + db * 32 + r32] = o[db][r] * ss[r] * sg; }
	v_mul_f32_e32 v83, v83, v84
	v_mul_f32_e32 v78, v78, v84
	v_mul_f32_e32 v79, v79, v84
	v_mul_f32_e32 v80, v80, v84
	v_mul_f32_e32 v81, v81, v84
	v_mul_f32_e32 v74, v74, v84
	v_mul_f32_e32 v75, v75, v84
	v_mul_f32_e32 v76, v76, v84
	v_mul_f32_e32 v77, v77, v84
	v_mul_f32_e32 v70, v70, v84
	v_mul_f32_e32 v71, v71, v84
	v_mul_f32_e32 v61, v61, v84
	v_mul_f32_e32 v72, v72, v84
	v_mul_f32_e32 v63, v63, v84
	v_mul_f32_e32 v64, v84, v64
	v_mul_f32_e32 v65, v84, v65
	v_mul_f32_e32 v50, v50, v85
	ds_write2_b32 v0, v83, v50 offset1:32
	v_mul_f32_e32 v50, v51, v30
	v_mul_f32_e32 v50, v50, v85
	ds_write2_b32 v0, v78, v50 offset0:128 offset1:160
	v_mul_f32_e32 v50, v52, v44
	v_mul_f32_e32 v50, v50, v85
	ds_write2_b32 v18, v79, v50 offset1:32
	v_mul_f32_e32 v50, v53, v47
	v_mul_f32_e32 v50, v50, v85
	ds_write2_b32 v18, v80, v50 offset0:128 offset1:160
	v_mul_f32_e32 v50, v54, v62
	v_mul_f32_e32 v43, v43, v85
	v_mul_f32_e32 v50, v50, v85
	ds_write2_b32 v21, v70, v43 offset0:128 offset1:160
	v_mul_f32_e32 v43, v59, v94
	ds_write2_b32 v19, v81, v50 offset1:32
	v_mul_f32_e32 v50, v55, v66
	v_mul_f32_e32 v43, v43, v85
	v_mul_f32_e32 v50, v50, v85
	ds_write2_b32 v22, v71, v43 offset1:32
	v_mul_f32_e32 v43, v45, v92
	ds_write2_b32 v19, v74, v50 offset0:128 offset1:160
	v_mul_f32_e32 v50, v56, v67
	v_mul_f32_e32 v43, v43, v85
	v_mul_f32_e32 v50, v50, v85
	ds_write2_b32 v22, v61, v43 offset0:128 offset1:160
	v_mul_f32_e32 v43, v46, v91
	ds_write2_b32 v20, v75, v50 offset1:32
	v_mul_f32_e32 v50, v57, v69
	v_mul_f32_e32 v43, v43, v85
	v_mul_f32_e32 v50, v50, v85
	ds_write2_b32 v23, v72, v43 offset1:32
	v_mul_f32_e32 v43, v60, v89
	ds_write2_b32 v20, v76, v50 offset0:128 offset1:160
	v_mul_f32_e32 v50, v58, v90
	v_mul_f32_e32 v43, v43, v85
	v_mul_f32_e32 v50, v50, v85
	ds_write2_b32 v23, v63, v43 offset0:128 offset1:160
	v_mul_f32_e32 v43, v48, v73
	ds_write2_b32 v21, v77, v50 offset1:32
	v_mul_f32_e32 v43, v43, v85
	ds_write2_b32 v15, v64, v43 offset1:32
	v_mul_f32_e32 v43, v49, v68
	v_mul_f32_e32 v43, v43, v85
	ds_write2_b32 v15, v65, v43 offset0:128 offset1:160
	v_mul_f32_e32 v50, v34, v86
	v_mul_f32_e32 v34, v35, v30
	v_mul_f32_e32 v49, v34, v86
	v_mul_f32_e32 v34, v36, v44
	v_mul_f32_e32 v48, v34, v86
	v_mul_f32_e32 v34, v37, v47
	v_mul_f32_e32 v46, v34, v86
	v_mul_f32_e32 v34, v38, v62
	v_mul_f32_e32 v38, v25, v86
	v_mul_f32_e32 v25, v26, v90
	v_mul_f32_e32 v37, v25, v86
	v_mul_f32_e32 v25, v41, v93
	v_mul_f32_e32 v45, v34, v86
	v_mul_f32_e32 v34, v39, v66
	v_mul_f32_e32 v36, v25, v86
	v_mul_f32_e32 v25, v28, v94
	v_mul_f32_e32 v43, v34, v86
	v_mul_f32_e32 v34, v40, v67
	v_mul_f32_e32 v35, v25, v86
	v_mul_f32_e32 v25, v29, v92
	v_mul_f32_e32 v39, v34, v86
	v_mul_f32_e32 v34, v25, v86
	v_mul_f32_e32 v25, v42, v91
	v_mul_f32_e32 v29, v25, v86
	v_mul_f32_e32 v25, v31, v89
	v_mul_f32_e32 v28, v25, v86
	v_mul_f32_e32 v25, v32, v73
	v_mul_f32_e32 v26, v25, v86
	v_mul_f32_e32 v25, v33, v68
	v_mul_f32_e32 v25, v25, v86
	v_mul_f32_e32 v2, v2, v87
	ds_write2_b32 v0, v50, v2 offset0:64 offset1:96
	v_mul_f32_e32 v2, v3, v30
	v_mul_f32_e32 v2, v2, v87
	ds_write2_b32 v0, v49, v2 offset0:192 offset1:224
	v_mul_f32_e32 v0, v4, v44
	v_mul_f32_e32 v0, v0, v87
	ds_write2_b32 v18, v48, v0 offset0:64 offset1:96
	v_mul_f32_e32 v0, v5, v47
	v_mul_f32_e32 v0, v0, v87
	ds_write2_b32 v18, v46, v0 offset0:192 offset1:224
	v_mul_f32_e32 v0, v6, v62
	v_mul_f32_e32 v0, v0, v87
	ds_write2_b32 v19, v45, v0 offset0:64 offset1:96
	v_mul_f32_e32 v0, v7, v66
	v_mul_f32_e32 v0, v0, v87
	ds_write2_b32 v19, v43, v0 offset0:192 offset1:224
	v_mul_f32_e32 v0, v8, v67
	v_mul_f32_e32 v0, v0, v87
	ds_write2_b32 v20, v39, v0 offset0:64 offset1:96
	v_mul_f32_e32 v0, v9, v69
	v_mul_f32_e32 v0, v0, v87
	ds_write2_b32 v20, v38, v0 offset0:192 offset1:224
	v_mul_f32_e32 v0, v10, v90
	v_mul_f32_e32 v0, v0, v87
	ds_write2_b32 v21, v37, v0 offset0:64 offset1:96
	v_mul_f32_e32 v0, v11, v93
	v_mul_f32_e32 v0, v0, v87
	ds_write2_b32 v21, v36, v0 offset0:192 offset1:224
	v_mul_f32_e32 v0, v12, v94
	v_mul_f32_e32 v0, v0, v87
	ds_write2_b32 v22, v35, v0 offset0:64 offset1:96
	v_mul_f32_e32 v0, v13, v92
	v_mul_f32_e32 v0, v0, v87
	ds_write2_b32 v22, v34, v0 offset0:192 offset1:224
	v_mul_f32_e32 v0, v14, v91
	v_mul_f32_e32 v0, v0, v87
	ds_write2_b32 v23, v29, v0 offset0:64 offset1:96
	v_mul_f32_e32 v0, v24, v89
	v_mul_f32_e32 v0, v0, v87
	ds_write2_b32 v23, v28, v0 offset0:192 offset1:224
	v_mul_f32_e32 v0, v16, v73
	v_mul_f32_e32 v0, v0, v87
	ds_write2_b32 v15, v26, v0 offset0:64 offset1:96
	v_mul_f32_e32 v0, v17, v68
	v_mul_f32_e32 v0, v0, v87
	ds_write2_b32 v15, v25, v0 offset0:192 offset1:224
	s_branch .LBB0_187
